# scan: loop-invariant LDS/shuffle addresses hoisted to phase set-up
# baseline (speedup 1.0000x reference)
; __device__ __forceinline__ int opaque_tid() { int t = threadIdx.x; asm volatile("" : "+v"(t)); return t; }
; template <bool DRY>
; __device__ __forceinline__ void phase_ssd_scan(const Args& a, int j, unsigned char* lds_raw) {
;     ...
;     const int tid = opaque_tid(), lane = tid & 63, wave = __builtin_amdgcn_readfirstlane(tid >> 6);
;     const int role = (wave == 1) ? 6 : ((wave == 6) ? 1 : wave);
;     const int c16 = lane & 15, q4 = lane >> 4, li = role >> 1, pi = role & 1;
;     for (int it = blockIdx.x; it < 256; it += gridDim.x) {
;         const int xc = it & 7, slot = it >> 3, pair = xc + 8 * (slot >> 3), sub = slot & 7;
;         SsdItem I; I.b = pair >> 3; I.g = pair & 7; I.h = I.g * 4 + (sub >> 1); I.ph = sub & 1;
;         I.Ah = -__expf(A_log[I.h]); I.Dh = Dp[I.h];
; #pragma unroll
;         for (int i = 0; i < 2; ++i) { I.offB[i] = (unsigned)(lane * BIGW + 4096 + I.g * 128 + (wave + 8 * i) * 8) * 2u; const int id = tid + 512 * i; I.offC[i] = (unsigned)((id >> 4) * BIGW + 5120 + I.g * 128 + (id & 15) * 8) * 2u; }
;         I.offX = (unsigned)(lane * BIGW + DI_ + I.h * 64 + I.ph * 32 + wave * 8) * 2u;
;         I.offZ = (unsigned)((16 * li + c16) * BIGW + I.h * 64 + I.ph * 32 + 16 * pi + 4 * q4) * 2u;
;         I.offDT = (unsigned)(lane * 32 + I.h) * 4u;
;         f32x4 st[2]; st[0] = (f32x4){0.f, 0.f, 0.f, 0.f}; st[1] = (f32x4){0.f, 0.f, 0.f, 0.f};
;         SsdRegs R0, R1; R0.rx = make_uint4(0, 0, 0, 0); R1.rx = make_uint4(0, 0, 0, 0);
;         ssd_load(R0, BIG, DT, I, 0, wave);
;         ssd_load(R1, BIG, DT, I, 1, wave);
.LBB0_705:
	s_cmp_lt_i32 s74, 2
	s_mov_b64 s[0:1], -1
	s_cbranch_scc1 .LBB0_752
	s_cmp_eq_u32 s74, 2
	s_cbranch_scc0 .LBB0_751
	v_readlane_b32 s0, v253, 63
	s_waitcnt vmcnt(0) lgkmcnt(0)
	v_mov_b32_e32 v2, v0
	v_readlane_b32 s1, v254, 0
	s_andn2_b64 vcc, exec, s[0:1]
	v_readfirstlane_b32 s0, v2
	s_cbranch_vccnz .LBB0_751
	s_cmp_eq_u32 s27, 0x100
	s_cselect_b32 s100, 2, 7
	s_cselect_b32 s101, 8, 2
	v_writelane_b32 v255, s74, 31
	v_writelane_b32 v255, s69, 32
	s_mov_b32 s2, s22
	v_writelane_b32 v255, s2, 12
	v_and_b32_e32 v5, 63, v2
	v_mov_b32_e32 v1, 0x1000
	v_writelane_b32 v255, s3, 13
	s_lshl_b32 s2, s22, 5
	s_ashr_i32 s3, s2, 31
	s_lshl_b64 s[2:3], s[2:3], 2
	s_waitcnt lgkmcnt(0)
	s_add_u32 s4, s54, s2
	s_addc_u32 s5, s55, s3
	s_add_u32 s2, s56, s2
	s_addc_u32 s3, s57, s3
	s_ashr_i32 s0, s0, 6
	s_cmp_lg_u32 s0, 6
	v_writelane_b32 v255, s4, 10
	s_cselect_b32 s1, s0, 1
	s_cmp_lg_u32 s0, 1
	v_writelane_b32 v255, s5, 11
	s_cselect_b32 s1, s1, 6
	v_writelane_b32 v255, s2, 22
	s_and_b32 s19, s1, 1
	s_ashr_i32 s1, s1, 1
	v_writelane_b32 v255, s3, 23
	s_lshl_b32 s36, s0, 4
	s_lshl_b32 s2, s19, 5
	s_cmp_lt_i32 s0, 4
	s_cselect_b64 s[4:5], -1, 0
	s_movk_i32 s22, 0x1800
	v_writelane_b32 v255, s4, 20
	s_cmp_gt_i32 s0, 3
	v_mad_u32_u24 v4, v5, s22, v1
	v_writelane_b32 v255, s5, 21
	s_cselect_b64 s[4:5], -1, 0
	v_bfe_u32 v10, v2, 4, 2
	v_lshl_add_u32 v1, s0, 3, v4
	v_writelane_b32 v255, s4, 24
	s_lshl_b32 s3, s0, 9
	s_lshl_b32 s0, s0, 5
	v_readlane_b32 s18, v254, 51
	v_lshlrev_b32_e32 v15, 3, v10
	v_writelane_b32 v255, s5, 25
	s_add_i32 s3, s3, 0
	s_add_i32 s4, s18, s0
	s_add_i32 s3, s3, 0x16800
	v_add_u32_e32 v19, s4, v15
	s_add_i32 s20, s36, 0
	s_add_i32 s4, s2, 0
	s_lshl_b32 s14, s19, 1
	v_and_b32_e32 v11, 15, v2
	v_mul_u32_u24_e32 v12, 0x1800, v5
	s_cmp_le_i32 s14, s1
	v_add3_u32 v108, v4, v12, s36
	v_lshl_or_b32 v4, s1, 4, v11
	v_add_u32_e32 v20, s4, v15
	s_movk_i32 s4, 0x90
	s_cselect_b64 s[88:89], -1, 0
	s_cmp_eq_u32 s14, s1
	v_mul_lo_u32 v32, v4, s4
	s_cselect_b64 s[4:5], -1, 0
	s_lshl_b32 s68, s19, 6
	s_or_b32 s16, s14, 1
	s_cmp_ge_i32 s14, s1
	s_movk_i32 s24, 0x110
	s_cselect_b64 s[84:85], -1, 0
	s_cmp_eq_u32 s16, s1
	v_lshlrev_b32_e32 v13, 3, v2
	v_mad_u32_u24 v110, v5, s24, 0
	v_ashrrev_i32_e32 v24, 4, v2
	v_add_u32_e32 v26, 0x200, v2
	v_and_b32_e32 v111, 48, v2
	s_cselect_b64 s[14:15], -1, 0
	s_lshl_b32 s69, s16, 5
	v_mov_b32_e32 v36, s18
	s_movk_i32 s18, 0x60
	v_readlane_b32 s25, v254, 52
	v_and_b32_e32 v14, 0x78, v13
	v_lshlrev_b32_e32 v109, s100, v5
	v_lshlrev_b32_e32 v18, 2, v5
	v_lshl_add_u32 v23, v5, 4, v110
	v_ashrrev_i32_e32 v26, 4, v26
	v_mul_u32_u24_e32 v29, 0x60, v5
	v_lshl_or_b32 v33, s19, 7, v111
	s_cmp_eq_u32 s19, 0
	v_writelane_b32 v255, s19, 18
	v_lshl_or_b32 v35, s19, 4, v11
	v_mul_lo_u32 v37, v4, s18
	v_cmp_gt_u32_e64 s[18:19], 16, v5
	v_mov_b32_e32 v5, s25
	v_mul_lo_u32 v114, v24, s22
	v_lshlrev_b32_e32 v10, 2, v10
	v_mad_u32_u24 v36, v35, s24, v36
	v_mad_u32_u24 v35, v35, s24, v5
	v_mul_lo_u32 v115, v26, s22
	v_or_b32_e32 v5, v114, v14
	v_bfe_u32 v17, v2, 2, 2
	v_and_b32_e32 v13, 24, v13
	v_cmp_gt_u32_e64 s[6:7], v10, v11
	v_cmp_lt_u32_e64 s[8:9], v10, v11
	v_or_b32_e32 v34, 2, v10
	v_or_b32_e32 v10, 3, v10
	v_add_u32_e32 v118, 0x1400, v5
	v_or_b32_e32 v5, v115, v14
	s_mul_i32 s1, s1, 0x30000
	s_movk_i32 s23, 0x3000
	v_or_b32_e32 v17, v15, v17
	v_add_u32_e32 v13, 0, v13
	v_lshlrev_b32_e32 v22, 4, v2
	v_cmp_gt_u32_e64 s[10:11], v34, v11
	v_cmp_gt_u32_e64 s[12:13], v10, v11
	v_lshl_or_b32 v10, s16, 4, v11
	v_lshl_or_b32 v34, s16, 6, v111
	s_movk_i32 s16, 0x120
	v_add_u32_e32 v120, 0x1400, v5
	v_mov_b32_e32 v5, s1
	v_and_b32_e32 v22, 0xf0, v22
	v_mul_u32_u24_e32 v28, 0x60, v17
	v_mul_lo_u32 v30, v4, s24
	v_add_u32_e32 v112, s91, v32
	v_or_b32_e32 v32, s2, v11
	s_movk_i32 s16, 0x110
	v_mad_u32_u24 v194, v17, s16, v13
	s_movk_i32 s16, 0x120
	v_mad_u32_u24 v17, v17, s16, v13
	s_cselect_b64 s[16:17], -1, 0
	s_add_i32 s21, s25, s0
	v_mad_u32_u24 v5, v11, s23, v5
	v_mul_lo_u32 v16, v4, s23
	v_mul_u32_u24_e32 v21, 0x110, v11
	v_add_u32_e32 v22, 0, v22
	v_mul_lo_u32 v25, v24, s24
	v_mul_lo_u32 v27, v26, s24
	v_add_u32_e32 v30, 0, v30
	v_lshlrev_b32_e32 v2, 2, v4
	v_add_u32_e32 v31, 0, v111
	v_mul_u32_u24_e32 v32, 0x110, v32
	v_mul_u32_u24_e32 v10, 0x110, v10
	v_add_u32_e32 v38, s21, v15
	s_add_i32 s21, s36, 0x2080
	v_or3_b32 v121, v5, s2, v15
	v_ashrrev_i32_e32 v5, 31, v4
	v_readlane_b32 s80, v253, 61
	s_mov_b32 s26, 0x9300000
	v_add_u32_e32 v113, v112, v15
	v_or3_b32 v116, v16, v15, s2
	v_or_b32_e32 v117, 0x1400, v14
	v_lshl_add_u32 v119, v12, 1, s21
	v_lshlrev_b64 v[74:75], 2, v[4:5]
	v_add_u32_e32 v122, v19, v21
	v_add_u32_e32 v123, v36, v111
	v_add_u32_e32 v124, v38, v21
	v_add_u32_e32 v125, v35, v111
	v_add_u32_e32 v126, s3, v18
	v_add_u32_e32 v127, v22, v25
	v_add_u32_e32 v128, s36, v23
	v_add_u32_e32 v129, v22, v27
	v_add_u32_e32 v130, s20, v29
	v_add_u32_e32 v131, v30, v111
	v_add_u32_e32 v132, s3, v2
	v_add_u32_e32 v133, v31, v32
	v_add_u32_e32 v134, s3, v33
	v_add_u32_e32 v135, v31, v10
	v_add_u32_e32 v136, s3, v34
	v_add_u32_e32 v137, s0, v17
	v_add_u32_e32 v138, v13, v28
	v_add_u32_e32 v194, s0, v194
	v_add_u32_e32 v83, 32, v138
	v_cndmask_b32_e64 v83, v83, v138, s[16:17]
	v_add_u32_e32 v139, v20, v37
	v_cmp_lt_i32_e32 vcc, v213, v208
	v_add_u32_e32 v190, v112, v111
	v_add_u32_e32 v191, s68, v113
	v_cndmask_b32_e32 v188, v207, v213, vcc
	v_cmp_lt_i32_e32 vcc, v214, v208
	v_lshlrev_b32_e32 v188, 2, v188
	v_add_u32_e32 v192, s69, v113
	v_cndmask_b32_e32 v189, v207, v214, vcc
	v_lshlrev_b32_e32 v189, 2, v189
	v_and_b32_e32 v76, 63, v0
	v_lshrrev_b32_e32 v77, 2, v76
	v_add_u32_e32 v77, s36, v77
	v_lshlrev_b32_e32 v195, 2, v77
	v_and_b32_e32 v76, 3, v76
	v_lshlrev_b32_e32 v76, 4, v76
	s_movk_i32 s2, 0x3000
	v_mad_u32_u24 v108, v77, s2, v76
	v_add_u32_e32 v108, 0x1000, v108
	s_movk_i32 s2, 0x60
	v_mad_u32_u24 v130, v77, s2, v76
	s_mov_b32 s72, s92
	s_mov_b32 s73, s92
	v_readlane_b32 s81, v253, 62
	s_branch .LBB0_710

; #define LAS __attribute__((address_space(3)))
; __device__ __forceinline__ unsigned pk2(float lo, float hi) { unsigned r; asm volatile("v_cvt_pk_bf16_f32 %0, %1, %2" : "=v"(r) : "v"(lo), "v"(hi)); return r; }
; template <int CTRL> __device__ __forceinline__ float dppz(float x) { return __builtin_bit_cast(float, __builtin_amdgcn_update_dpp(0, __builtin_bit_cast(int, x), CTRL, 0xf, 0xf, true)); }
; template <bool DRY>
; __device__ __forceinline__ void ssd_chunk(SsdRegs& R, f32x4 (&st)[2], LAS unsigned char* L, bf16_t* BIG, const float* DT, float* SSQY, const SsdItem& I, int c, int tid, int lane, int wave, int li, int pi, int c16, int q4) {
;     ...
;     const float dtl = R.rdt;
;     float acs = dtl * I.Ah;
;     acs += dppz<0x111>(acs); acs += dppz<0x112>(acs); acs += dppz<0x114>(acs); acs += dppz<0x118>(acs);
;     acs += __builtin_bit_cast(float, __builtin_amdgcn_update_dpp(0, __builtin_bit_cast(int, acs), 0x142, 0xa, 0xf, false));
;     acs += __builtin_bit_cast(float, __builtin_amdgcn_update_dpp(0, __builtin_bit_cast(int, acs), 0x143, 0xc, 0xf, false));
;     const float tot = __builtin_bit_cast(float, __builtin_amdgcn_readlane(__builtin_bit_cast(int, acs), 63));
;     const float wl = dtl * __expf(tot - acs), etot = __expf(tot);
;     LAS unsigned char* SCW = L + SCT + wave * 512;
;     *(LAS float*)(SCW + lane * 4) = acs; *(LAS float*)(SCW + 256 + lane * 4) = dtl;
; #pragma unroll
;     for (int pt = 0; pt < 2; ++pt) { u32x2 w; w.x = pk2(st[pt][0], st[pt][1]); w.y = pk2(st[pt][2], st[pt][3]); *(LAS u32x2*)(L + SB + (16 * pt + c16) * PC + (16 * wave + 4 * q4) * 2) = w; }
; #pragma unroll
;     for (int i = 0; i < 2; ++i) {
;         const int id = tid + 512 * i; *(LAS u32x4*)(L + CS + (id >> 4) * PC + (id & 15) * 16) = (u32x4){R.rc[i].x, R.rc[i].y, R.rc[i].z, R.rc[i].w};
;         const int n8 = wave + 8 * i; *(LAS u32x4*)(L + BS + lane * PC + n8 * 16) = (u32x4){R.rb[i].x, R.rb[i].y, R.rb[i].z, R.rb[i].w};
;         float f[8]; unpack8(R.rb[i], f);
;         u32x4 bwv; bwv.x = pk2(f[0] * wl, f[1] * wl); bwv.y = pk2(f[2] * wl, f[3] * wl); bwv.z = pk2(f[4] * wl, f[5] * wl); bwv.w = pk2(f[6] * wl, f[7] * wl);
;         *(LAS u32x4*)(L + BW + lane * PB + n8 * 16) = bwv;
;     }
;     if (wave < 4) *(LAS u32x4*)(L + XI + lane * PX + wave * 16) = (u32x4){R.rx.x, R.rx.y, R.rx.z, R.rx.w};
;     const u32x2 zc = R.rz;
;     __syncthreads();
.LBB0_720:
	s_waitcnt vmcnt(6)
	v_mul_f32_e64 v65, v140, -v141
	v_mov_b32_e32 v66, 0
	v_mov_b32_dpp v65, v65 row_shr:1 row_mask:0xf bank_mask:0xf bound_ctrl:1
	v_fma_f32 v65, v140, -v141, v65
	s_and_b64 vcc, exec, s[20:21]
	s_nop 0
	v_add_f32_dpp v65, v65, v65 row_shr:2 row_mask:0xf bank_mask:0xf bound_ctrl:1
	s_nop 1
	v_add_f32_dpp v65, v65, v65 row_shr:4 row_mask:0xf bank_mask:0xf bound_ctrl:1
	s_nop 1
	v_add_f32_dpp v65, v65, v65 row_shr:8 row_mask:0xf bank_mask:0xf bound_ctrl:1
	s_nop 1
	v_mov_b32_dpp v66, v65 row_bcast:15 row_mask:0xa bank_mask:0xf
	v_add_f32_e32 v65, v65, v66
	v_mov_b32_e32 v66, 0
	s_nop 1
	v_mov_b32_dpp v66, v65 row_bcast:31 row_mask:0xc bank_mask:0xf
	v_add_f32_e32 v65, v65, v66
	ds_write2st64_b32 v126, v65, v140 offset1:1
	v_readlane_b32 s3, v65, 63
	v_cvt_pk_bf16_f32 v58, v50, v58
	v_cvt_pk_bf16_f32 v59, v59, v61
	ds_write_b64 v122, v[58:59]
	v_cvt_pk_bf16_f32 v58, v60, v62
	v_cvt_pk_bf16_f32 v59, v63, v64
	s_nop 0
	v_sub_f32_e32 v66, s3, v65
	v_exp_f32_e32 v66, v66
	ds_write_b64 v122, v[58:59] offset:4352
	ds_write_b128 v127, v[14:17]
	ds_write_b128 v127, v[10:13] offset:17408
	v_mul_f32_e32 v62, v140, v66
	ds_write_b128 v129, v[22:25]
	ds_write_b128 v129, v[18:21] offset:17408
	s_cbranch_vccnz .LBB0_722
	ds_bpermute_b32 v82, v195, v62
	ds_write_b128 v130, v[26:29] offset:53248
	v_lshlrev_b32_e32 v58, 16, v26
	v_and_b32_e32 v59, 0xffff0000, v26
	v_lshlrev_b32_e32 v60, 16, v27
	v_and_b32_e32 v61, 0xffff0000, v27
	v_lshlrev_b32_e32 v64, 16, v28
	v_and_b32_e32 v65, 0xffff0000, v28
	v_lshlrev_b32_e32 v66, 16, v29
	v_and_b32_e32 v67, 0xffff0000, v29
	s_waitcnt lgkmcnt(1)
	v_pk_mul_f32 v[58:59], v[58:59], v[82:83] op_sel_hi:[1,0]
	v_pk_mul_f32 v[60:61], v[60:61], v[82:83] op_sel_hi:[1,0]
	v_pk_mul_f32 v[64:65], v[64:65], v[82:83] op_sel_hi:[1,0]
	v_pk_mul_f32 v[66:67], v[66:67], v[82:83] op_sel_hi:[1,0]
	v_cvt_pk_bf16_f32 v58, v58, v59
	v_cvt_pk_bf16_f32 v59, v60, v61
	v_cvt_pk_bf16_f32 v60, v64, v65
	v_cvt_pk_bf16_f32 v61, v66, v67
	ds_write_b128 v130, v[58:61] offset:34816

; #define LAS __attribute__((address_space(3)))
; __device__ __forceinline__ unsigned pk2(float lo, float hi) { unsigned r; asm volatile("v_cvt_pk_bf16_f32 %0, %1, %2" : "=v"(r) : "v"(lo), "v"(hi)); return r; }
; template <bool DRY>
; __device__ __forceinline__ void ssd_chunk(SsdRegs& R, f32x4 (&st)[2], LAS unsigned char* L, bf16_t* BIG, const float* DT, float* SSQY, const SsdItem& I, int c, int tid, int lane, int wave, int li, int pi, int c16, int q4) {
;     ...
;         for (int t = 0; t < 2; ++t) {
;             const int si = 2 * pi + t;
;             u32x2 w; w.x = 0u; w.y = 0u;
;             if (si <= li) {
;                 f32x4 d = (f32x4){0.f, 0.f, 0.f, 0.f};
; #pragma unroll
;                 for (int kk = 0; kk < 4; ++kk) d = __builtin_amdgcn_mfma_f32_16x16x32_bf16(SSD_FRAG(BS, PC, 16 * si, kk), cfr[kk], d, 0, 0, 0);
;                 float gv[4];
;                 const f32x4 acs_s = *(const LAS f32x4*)(SCW + (16 * si + 4 * q4) * 4), dt_s = *(const LAS f32x4*)(SCW + 256 + (16 * si + 4 * q4) * 4);
; #pragma unroll
;                 for (int e = 0; e < 4; ++e) gv[e] = d[e] * __expf(acs_l - acs_s[e]) * dt_s[e];
;                 if (si == li) {
; #pragma unroll
;                     for (int e = 0; e < 4; ++e) gv[e] = (4 * q4 + e <= c16) ? gv[e] : 0.f;
;                 }
;                 w.x = pk2(gv[0], gv[1]); w.y = pk2(gv[2], gv[3]);
;             }
;             *(LAS u32x2*)(L + GG + l * PT + (16 * si + 4 * q4) * 2) = w;
.LBB0_729:
	ds_write_b64 v191, v[106:107]
	v_cndmask_b32_e64 v106, 0, 1, s[84:85]
	v_cmp_ne_u32_e64 s[24:25], 1, v106
	s_andn2_b64 vcc, exec, s[84:85]
	s_mov_b64 s[0:1], -1
	s_cbranch_vccnz .LBB0_731
	s_mov_b64 s[0:1], 0

; #define LAS __attribute__((address_space(3)))
; __device__ __forceinline__ float bf_lo(unsigned w) { return __uint_as_float(w << 16); }
; template <bool DRY>
; __device__ __forceinline__ void ssd_chunk(SsdRegs& R, f32x4 (&st)[2], LAS unsigned char* L, bf16_t* BIG, const float* DT, float* SSQY, const SsdItem& I, int c, int tid, int lane, int wave, int li, int pi, int c16, int q4) {
;     ...
;     f32x4 stn[2];
;     bf16x8 xfr[2][2], bwf[2];
; #pragma unroll
;     for (int kk = 0; kk < 2; ++kk) { bwf[kk] = SSD_TR(BW, PB, trB, wave, kk); xfr[0][kk] = SSD_TR(XI, PX, trX, 0, kk); xfr[1][kk] = SSD_TR(XI, PX, trX, 1, kk); }
; #pragma unroll
;     for (int pt = 0; pt < 2; ++pt) {
;         f32x4 d = st[pt] * etot;
; #pragma unroll
;         for (int kk = 0; kk < 2; ++kk) d = __builtin_amdgcn_mfma_f32_16x16x32_bf16(bwf[kk], xfr[pt][kk], d, 0, 0, 0);
;         stn[pt] = d;
;     }
;     const bf16x8 xy0 = pi ? xfr[1][0] : xfr[0][0], xy1 = pi ? xfr[1][1] : xfr[0][1];
;     st[0] = stn[0]; st[1] = stn[1];
;     __syncthreads();
;     {
;         f32x4 d1 = (f32x4){0.f, 0.f, 0.f, 0.f}, d2 = (f32x4){0.f, 0.f, 0.f, 0.f};
; #pragma unroll
;         for (int kk = 0; kk < 2; ++kk) d1 = __builtin_amdgcn_mfma_f32_16x16x32_bf16(kk ? xy1 : xy0, SSD_FRAG(GG, PT, 16 * li, kk), d1, 0, 0, 0);
; #pragma unroll
;         for (int kk = 0; kk < 4; ++kk) d2 = __builtin_amdgcn_mfma_f32_16x16x32_bf16(SSD_FRAG(SB, PC, 16 * pi, kk), cfr[kk], d2, 0, 0, 0);
;         const int l = 16 * li + c16; const float ea_l = __expf(*(const LAS float*)(SCW + l * 4));
;         const float zf[4] = {bf_lo(zc.x), bf_hi(zc.x), bf_lo(zc.y), bf_hi(zc.y)};
;         float yg[4], sq = 0.f;
;         const u32x2 xr = *(const LAS u32x2*)(L + XI + l * PX + (16 * pi + 4 * q4) * 2);
;         const float xs[4] = {bf_lo(xr.x), bf_hi(xr.x), bf_lo(xr.y), bf_hi(xr.y)};
; #pragma unroll
;         for (int e = 0; e < 4; ++e) { const float xv = xs[e];
;             const float y = d1[e] + ea_l * d2[e] + I.Dh * xv; yg[e] = y * silu_f(zf[e]); sq += yg[e] * yg[e]; }
;         u32x2 w; w.x = pk2(yg[0], yg[1]); w.y = pk2(yg[2], yg[3]);
;         if (!DRY) *(u32x2*)((char*)BIG + row0 * (BIGW * 2) + I.offZ) = w;
;         sq += __shfl_xor(sq, 16); sq += __shfl_xor(sq, 32);
;         if (DRY) { if (sq == 12345.678f) SSQY[0] = 1.f; } else if (q4 == 0) SSQY[(size_t)(I.h * 4 + I.ph * 2 + pi) * M_ + row0 + l] = sq;
;     }
.LBB0_733:
	s_waitcnt lgkmcnt(1)
	ds_write_b64 v192, v[106:107]
	ds_read_b64_tr_b16 v[146:147], v194 offset:17408
	ds_read_b64_tr_b16 v[148:149], v194 offset:18496
	v_exp_f32_e32 v76, s3
	ds_read_b64_tr_b16 v[152:153], v138 offset:35200
	ds_read_b64_tr_b16 v[150:151], v138 offset:34816
	ds_read_b64_tr_b16 v[154:155], v194 offset:26112
	ds_read_b64_tr_b16 v[156:157], v194 offset:27200
	ds_read_b64_tr_b16 v[158:159], v138 offset:37888
	ds_read_b64_tr_b16 v[160:161], v138 offset:38272
	ds_read_b64_tr_b16 v[162:163], v138 offset:34848
	ds_read_b64_tr_b16 v[164:165], v138 offset:35232
	ds_read_b64_tr_b16 v[166:167], v138 offset:37920
	ds_read_b64_tr_b16 v[168:169], v138 offset:38304
	v_pk_mul_f32 v[52:53], v[52:53], v[76:77] op_sel_hi:[1,0]
	v_pk_mul_f32 v[50:51], v[50:51], v[76:77] op_sel_hi:[1,0]
	v_pk_mul_f32 v[56:57], v[56:57], v[76:77] op_sel_hi:[1,0]
	v_pk_mul_f32 v[54:55], v[54:55], v[76:77] op_sel_hi:[1,0]
	s_waitcnt lgkmcnt(8)
	v_mfma_f32_16x16x32_bf16 v[50:53], v[146:149], v[150:153], v[50:53]
	ds_read_b64_tr_b16 v[196:197], v83 offset:53248
	ds_read_b64_tr_b16 v[198:199], v83 offset:53632
	ds_read_b64_tr_b16 v[200:201], v83 offset:56320
	ds_read_b64_tr_b16 v[202:203], v83 offset:56704
	s_waitcnt lgkmcnt(0)
	s_barrier
	v_mfma_f32_16x16x32_bf16 v[54:57], v[146:149], v[162:165], v[54:57]
	v_mfma_f32_16x16x32_bf16 v[50:53], v[154:157], v[158:161], v[50:53]
	v_mfma_f32_16x16x32_bf16 v[54:57], v[154:157], v[166:169], v[54:57]
	ds_read_b128 v[150:153], v190
	ds_read_b128 v[154:157], v123
	ds_read_b32 v76, v132
	s_waitcnt lgkmcnt(2)
	v_mfma_f32_16x16x32_bf16 v[146:149], v[196:199], v[150:153], 0
	ds_read_b128 v[150:153], v123 offset:64
	s_waitcnt lgkmcnt(2)
	v_mfma_f32_16x16x32_bf16 v[70:73], v[154:157], v[70:73], 0
	ds_read_b128 v[154:157], v123 offset:128
	s_waitcnt lgkmcnt(1)
	v_mfma_f32_16x16x32_bf16 v[66:69], v[150:153], v[66:69], v[70:73]
	s_nop 4
	ds_read_b128 v[70:73], v123 offset:192
	s_waitcnt lgkmcnt(1)
	v_mfma_f32_16x16x32_bf16 v[62:65], v[154:157], v[62:65], v[66:69]
	s_nop 2
	ds_read_b128 v[66:69], v190 offset:64
	s_waitcnt lgkmcnt(1)
	v_mfma_f32_16x16x32_bf16 v[58:61], v[70:73], v[58:61], v[62:65]
	v_lshlrev_b32_e32 v70, 16, v96
	s_nop 1
	v_exp_f32_e32 v72, v76
	v_mul_f32_e32 v62, 0xbfb8aa3b, v70
	v_exp_f32_e32 v71, v62
	s_waitcnt lgkmcnt(0)
	v_mfma_f32_16x16x32_bf16 v[62:65], v[200:203], v[66:69], v[146:149]
	ds_read_b64 v[66:67], v139 offset:53248
	s_nop 6
	v_fma_f32 v62, v58, v72, v62
	v_add_f32_e32 v58, 1.0, v71
	v_rcp_f32_e32 v76, v58
	v_and_b32_e32 v58, 0xffff0000, v96
	v_mul_f32_e32 v68, 0xbfb8aa3b, v58
	v_exp_f32_e32 v73, v68
	s_waitcnt lgkmcnt(0)
	v_lshlrev_b32_e32 v71, 16, v66
	v_pk_mul_f32 v[68:69], v[76:77], v[70:71]
	v_fma_f32 v63, v59, v72, v63
	v_add_f32_e32 v62, v62, v69
	v_add_f32_e32 v69, 1.0, v73
	v_rcp_f32_e32 v76, v69
	v_and_b32_e32 v59, 0xffff0000, v66
	v_mul_f32_e32 v62, v68, v62
	v_fma_f32 v64, v60, v72, v64
	v_pk_mul_f32 v[58:59], v[76:77], v[58:59]
	v_fmac_f32_e32 v65, v61, v72
	v_add_f32_e32 v59, v63, v59
	v_mul_f32_e32 v63, v58, v59
	v_lshlrev_b32_e32 v58, 16, v97
	v_mul_f32_e32 v59, 0xbfb8aa3b, v58
	v_exp_f32_e32 v68, v59
	v_lshlrev_b32_e32 v59, 16, v67
	v_and_b32_e32 v61, 0xffff0000, v67
	v_mul_f32_e32 v66, v63, v63
	v_add_f32_e32 v60, 1.0, v68
	v_rcp_f32_e32 v76, v60
	v_and_b32_e32 v60, 0xffff0000, v97
	v_mul_f32_e32 v68, 0xbfb8aa3b, v60
	v_exp_f32_e32 v68, v68
	v_pk_mul_f32 v[58:59], v[76:77], v[58:59]
	v_fmac_f32_e32 v66, v62, v62
	v_add_f32_e32 v59, v64, v59
	v_mul_f32_e32 v64, v58, v59
	v_add_f32_e32 v58, 1.0, v68
	v_rcp_f32_e32 v76, v58
	v_fmac_f32_e32 v66, v64, v64
	v_pk_mul_f32 v[58:59], v[76:77], v[60:61]
	s_nop 0
	v_add_f32_e32 v59, v65, v59
	v_mul_f32_e32 v58, v58, v59
	v_fmac_f32_e32 v66, v58, v58
	ds_bpermute_b32 v59, v188, v66
	v_cvt_pk_bf16_f32 v60, v62, v63
	v_cvt_pk_bf16_f32 v61, v64, v58
	s_waitcnt lgkmcnt(0)
	v_add_f32_e32 v58, v66, v59
	ds_bpermute_b32 v59, v189, v58
	global_store_dwordx2 v[78:79], v[60:61], off
	s_mov_b64 s[0:1], 0xc0000
	v_lshl_add_u64 v[78:79], v[78:79], 0, s[0:1]
	s_and_saveexec_b64 s[0:1], s[18:19]
	s_cbranch_execz .LBB0_735
	s_waitcnt lgkmcnt(0)
	v_add_f32_e32 v60, v58, v59
	global_store_dword v[90:91], v60, off

; #define LAS __attribute__((address_space(3)))
; __device__ __forceinline__ unsigned pk2(float lo, float hi) { unsigned r; asm volatile("v_cvt_pk_bf16_f32 %0, %1, %2" : "=v"(r) : "v"(lo), "v"(hi)); return r; }
; template <bool DRY>
; __device__ __forceinline__ void ssd_chunk(SsdRegs& R, f32x4 (&st)[2], LAS unsigned char* L, bf16_t* BIG, const float* DT, float* SSQY, const SsdItem& I, int c, int tid, int lane, int wave, int li, int pi, int c16, int q4) {
;     ...
;     bf16x8 cfr[4];
; #pragma unroll
;     for (int kk = 0; kk < 4; ++kk) cfr[kk] = SSD_FRAG(CS, PC, 16 * li, kk);
;     {
;         const int l = 16 * li + c16; const float acs_l = *(const LAS float*)(SCW + l * 4);
; #pragma unroll
;         for (int t = 0; t < 2; ++t) {
;             const int si = 2 * pi + t;
;             u32x2 w; w.x = 0u; w.y = 0u;
;             if (si <= li) {
;                 f32x4 d = (f32x4){0.f, 0.f, 0.f, 0.f};
; #pragma unroll
;                 for (int kk = 0; kk < 4; ++kk) d = __builtin_amdgcn_mfma_f32_16x16x32_bf16(SSD_FRAG(BS, PC, 16 * si, kk), cfr[kk], d, 0, 0, 0);
;                 float gv[4];
;                 const f32x4 acs_s = *(const LAS f32x4*)(SCW + (16 * si + 4 * q4) * 4), dt_s = *(const LAS f32x4*)(SCW + 256 + (16 * si + 4 * q4) * 4);
; #pragma unroll
;                 for (int e = 0; e < 4; ++e) gv[e] = d[e] * __expf(acs_l - acs_s[e]) * dt_s[e];
;                 if (si == li) {
; #pragma unroll
;                     for (int e = 0; e < 4; ++e) gv[e] = (4 * q4 + e <= c16) ? gv[e] : 0.f;
;                 }
;                 w.x = pk2(gv[0], gv[1]); w.y = pk2(gv[2], gv[3]);
;             }
;             *(LAS u32x2*)(L + GG + l * PT + (16 * si + 4 * q4) * 2) = w;
.LBB0_742:
	ds_read_b128 v[70:73], v131
	ds_read_b128 v[66:69], v131 offset:64
	ds_read_b128 v[62:65], v131 offset:128
	ds_read_b128 v[58:61], v131 offset:192
	ds_read_b32 v76, v132
	v_mov_b32_e32 v100, 0
	s_and_b64 vcc, exec, s[22:23]
	v_mov_b32_e32 v101, v100
	s_cbranch_vccnz .LBB0_748
	ds_read_b128 v[100:103], v133 offset:17408
	ds_read_b128 v[148:151], v133 offset:17472
	ds_read_b128 v[176:179], v133 offset:17536
	ds_read_b128 v[180:183], v133 offset:17600
	ds_read_b128 v[184:187], v134
	ds_read_b128 v[152:155], v134 offset:256
	s_waitcnt lgkmcnt(5)
	v_mfma_f32_16x16x32_bf16 v[100:103], v[100:103], v[70:73], 0
	s_waitcnt lgkmcnt(4)
	v_mfma_f32_16x16x32_bf16 v[100:103], v[148:151], v[66:69], v[100:103]
	s_waitcnt lgkmcnt(3)
	v_mfma_f32_16x16x32_bf16 v[100:103], v[176:179], v[62:65], v[100:103]
	s_waitcnt lgkmcnt(2)
	v_mfma_f32_16x16x32_bf16 v[100:103], v[180:183], v[58:61], v[100:103]
	s_nop 1
	s_waitcnt lgkmcnt(1)
	v_sub_f32_e32 v104, v76, v184
	v_sub_f32_e32 v105, v76, v185
	v_exp_f32_e32 v104, v104
	v_exp_f32_e32 v105, v105
	s_nop 0
	v_pk_mul_f32 v[100:101], v[100:101], v[104:105]
	v_sub_f32_e32 v104, v76, v186
	v_sub_f32_e32 v105, v76, v187
	v_exp_f32_e32 v104, v104
	v_exp_f32_e32 v105, v105
	s_waitcnt lgkmcnt(0)
	v_pk_mul_f32 v[100:101], v[152:153], v[100:101]
	v_pk_mul_f32 v[102:103], v[102:103], v[104:105]
	s_nop 0
	v_pk_mul_f32 v[102:103], v[154:155], v[102:103]
	v_cndmask_b32_e64 v104, v100, 0, s[6:7]
	v_cndmask_b32_e64 v105, 0, v101, s[8:9]
	v_cndmask_b32_e64 v142, v102, 0, s[10:11]
	v_cndmask_b32_e64 v148, v103, 0, s[12:13]
	v_cndmask_b32_e64 v100, v100, v104, s[4:5]
	v_cndmask_b32_e64 v101, v101, v105, s[4:5]
	v_cndmask_b32_e64 v102, v102, v142, s[4:5]
	v_cndmask_b32_e64 v103, v103, v148, s[4:5]
	v_cvt_pk_bf16_f32 v100, v100, v101
	v_cvt_pk_bf16_f32 v101, v102, v103
	s_and_b64 vcc, exec, s[24:25]
	s_mov_b64 s[0:1], -1
	ds_write_b64 v191, v[100:101]
	s_cbranch_vccz .LBB0_749

; #define LAS __attribute__((address_space(3)))
; __device__ __forceinline__ float bf_lo(unsigned w) { return __uint_as_float(w << 16); }
; template <bool DRY>
; __device__ __forceinline__ void ssd_chunk(SsdRegs& R, f32x4 (&st)[2], LAS unsigned char* L, bf16_t* BIG, const float* DT, float* SSQY, const SsdItem& I, int c, int tid, int lane, int wave, int li, int pi, int c16, int q4) {
;     ...
;     f32x4 stn[2];
;     bf16x8 xfr[2][2], bwf[2];
; #pragma unroll
;     for (int kk = 0; kk < 2; ++kk) { bwf[kk] = SSD_TR(BW, PB, trB, wave, kk); xfr[0][kk] = SSD_TR(XI, PX, trX, 0, kk); xfr[1][kk] = SSD_TR(XI, PX, trX, 1, kk); }
; #pragma unroll
;     for (int pt = 0; pt < 2; ++pt) {
;         f32x4 d = st[pt] * etot;
; #pragma unroll
;         for (int kk = 0; kk < 2; ++kk) d = __builtin_amdgcn_mfma_f32_16x16x32_bf16(bwf[kk], xfr[pt][kk], d, 0, 0, 0);
;         stn[pt] = d;
;     }
;     const bf16x8 xy0 = pi ? xfr[1][0] : xfr[0][0], xy1 = pi ? xfr[1][1] : xfr[0][1];
;     st[0] = stn[0]; st[1] = stn[1];
;     __syncthreads();
;     {
;         f32x4 d1 = (f32x4){0.f, 0.f, 0.f, 0.f}, d2 = (f32x4){0.f, 0.f, 0.f, 0.f};
; #pragma unroll
;         for (int kk = 0; kk < 2; ++kk) d1 = __builtin_amdgcn_mfma_f32_16x16x32_bf16(kk ? xy1 : xy0, SSD_FRAG(GG, PT, 16 * li, kk), d1, 0, 0, 0);
; #pragma unroll
;         for (int kk = 0; kk < 4; ++kk) d2 = __builtin_amdgcn_mfma_f32_16x16x32_bf16(SSD_FRAG(SB, PC, 16 * pi, kk), cfr[kk], d2, 0, 0, 0);
;         const int l = 16 * li + c16; const float ea_l = __expf(*(const LAS float*)(SCW + l * 4));
;         const float zf[4] = {bf_lo(zc.x), bf_hi(zc.x), bf_lo(zc.y), bf_hi(zc.y)};
;         float yg[4], sq = 0.f;
;         const u32x2 xr = *(const LAS u32x2*)(L + XI + l * PX + (16 * pi + 4 * q4) * 2);
;         const float xs[4] = {bf_lo(xr.x), bf_hi(xr.x), bf_lo(xr.y), bf_hi(xr.y)};
; #pragma unroll
;         for (int e = 0; e < 4; ++e) { const float xv = xs[e];
;             const float y = d1[e] + ea_l * d2[e] + I.Dh * xv; yg[e] = y * silu_f(zf[e]); sq += yg[e] * yg[e]; }
;         u32x2 w; w.x = pk2(yg[0], yg[1]); w.y = pk2(yg[2], yg[3]);
;         if (!DRY) *(u32x2*)((char*)BIG + row0 * (BIGW * 2) + I.offZ) = w;
;         sq += __shfl_xor(sq, 16); sq += __shfl_xor(sq, 32);
;         if (DRY) { if (sq == 12345.678f) SSQY[0] = 1.f; } else if (q4 == 0) SSQY[(size_t)(I.h * 4 + I.ph * 2 + pi) * M_ + row0 + l] = sq;
;     }
.LBB0_746:
	s_waitcnt lgkmcnt(1)
	v_exp_f32_e32 v76, s3
	ds_write_b64 v192, v[100:101]
	ds_read_b64_tr_b16 v[100:101], v194 offset:17408
	ds_read_b64_tr_b16 v[102:103], v194 offset:18496
	ds_read_b64_tr_b16 v[150:151], v138 offset:35200
	ds_read_b64_tr_b16 v[148:149], v138 offset:34816
	ds_read_b64_tr_b16 v[152:153], v194 offset:26112
	ds_read_b64_tr_b16 v[154:155], v194 offset:27200
	ds_read_b64_tr_b16 v[156:157], v138 offset:37888
	ds_read_b64_tr_b16 v[158:159], v138 offset:38272
	ds_read_b64_tr_b16 v[162:163], v138 offset:35232
	ds_read_b64_tr_b16 v[160:161], v138 offset:34848
	ds_read_b64_tr_b16 v[166:167], v138 offset:38304
	v_pk_mul_f32 v[52:53], v[52:53], v[76:77] op_sel_hi:[1,0]
	v_pk_mul_f32 v[50:51], v[50:51], v[76:77] op_sel_hi:[1,0]
	ds_read_b64_tr_b16 v[164:165], v138 offset:37920
	v_pk_mul_f32 v[56:57], v[56:57], v[76:77] op_sel_hi:[1,0]
	v_pk_mul_f32 v[54:55], v[54:55], v[76:77] op_sel_hi:[1,0]
	s_waitcnt lgkmcnt(8)
	v_mfma_f32_16x16x32_bf16 v[50:53], v[100:103], v[148:151], v[50:53]
	ds_read_b64_tr_b16 v[196:197], v83 offset:59392
	ds_read_b64_tr_b16 v[198:199], v83 offset:59776
	ds_read_b64_tr_b16 v[200:201], v83 offset:62464
	ds_read_b64_tr_b16 v[202:203], v83 offset:62848
	s_waitcnt lgkmcnt(0)
	s_barrier
	v_mfma_f32_16x16x32_bf16 v[54:57], v[100:103], v[160:163], v[54:57]
	v_mfma_f32_16x16x32_bf16 v[50:53], v[152:155], v[156:159], v[50:53]
	ds_read_b128 v[148:151], v190
	v_mfma_f32_16x16x32_bf16 v[54:57], v[152:155], v[164:167], v[54:57]
	ds_read_b128 v[152:155], v125
	s_waitcnt lgkmcnt(1)
	v_mfma_f32_16x16x32_bf16 v[100:103], v[196:199], v[148:151], 0
	ds_read_b128 v[148:151], v125 offset:64
	s_waitcnt lgkmcnt(1)
	v_mfma_f32_16x16x32_bf16 v[70:73], v[152:155], v[70:73], 0
	ds_read_b128 v[152:155], v125 offset:128
	s_waitcnt lgkmcnt(1)
	v_mfma_f32_16x16x32_bf16 v[66:69], v[148:151], v[66:69], v[70:73]
	s_nop 4
	ds_read_b128 v[70:73], v125 offset:192
	ds_read_b32 v76, v132
	s_waitcnt lgkmcnt(2)
	v_mfma_f32_16x16x32_bf16 v[62:65], v[152:155], v[62:65], v[66:69]
	s_nop 2
	v_lshlrev_b32_e32 v68, 16, v92
	s_waitcnt lgkmcnt(1)
	v_mfma_f32_16x16x32_bf16 v[58:61], v[70:73], v[58:61], v[62:65]
	v_mul_f32_e32 v69, 0xbfb8aa3b, v68
	v_exp_f32_e32 v69, v69
	s_waitcnt lgkmcnt(0)
	v_exp_f32_e32 v70, v76
	ds_read_b128 v[62:65], v190 offset:64
	ds_read_b64 v[66:67], v139 offset:59392
	s_waitcnt lgkmcnt(1)
	v_mfma_f32_16x16x32_bf16 v[62:65], v[200:203], v[62:65], v[100:103]
	s_nop 7
	v_fma_f32 v62, v58, v70, v62
	v_add_f32_e32 v58, 1.0, v69
	v_rcp_f32_e32 v76, v58
	v_and_b32_e32 v58, 0xffff0000, v92
	v_mul_f32_e32 v69, 0xbfb8aa3b, v58
	v_exp_f32_e32 v71, v69
	s_waitcnt lgkmcnt(0)
	v_lshlrev_b32_e32 v69, 16, v66
	v_pk_mul_f32 v[68:69], v[76:77], v[68:69]
	v_fma_f32 v63, v59, v70, v63
	v_add_f32_e32 v62, v62, v69
	v_add_f32_e32 v69, 1.0, v71
	v_rcp_f32_e32 v76, v69
	v_and_b32_e32 v59, 0xffff0000, v66
	v_mul_f32_e32 v62, v68, v62
	v_fma_f32 v64, v60, v70, v64
	v_pk_mul_f32 v[58:59], v[76:77], v[58:59]
	v_fmac_f32_e32 v65, v61, v70
	v_add_f32_e32 v59, v63, v59
	v_mul_f32_e32 v63, v58, v59
	v_lshlrev_b32_e32 v58, 16, v93
	v_mul_f32_e32 v59, 0xbfb8aa3b, v58
	v_exp_f32_e32 v68, v59
	v_lshlrev_b32_e32 v59, 16, v67
	v_and_b32_e32 v61, 0xffff0000, v67
	v_mul_f32_e32 v66, v63, v63
	v_add_f32_e32 v60, 1.0, v68
	v_rcp_f32_e32 v76, v60
	v_and_b32_e32 v60, 0xffff0000, v93
	v_mul_f32_e32 v68, 0xbfb8aa3b, v60
	v_exp_f32_e32 v68, v68
	v_pk_mul_f32 v[58:59], v[76:77], v[58:59]
	v_fmac_f32_e32 v66, v62, v62
	v_add_f32_e32 v59, v64, v59
	v_mul_f32_e32 v64, v58, v59
	v_add_f32_e32 v58, 1.0, v68
	v_rcp_f32_e32 v76, v58
	v_fmac_f32_e32 v66, v64, v64
	v_pk_mul_f32 v[58:59], v[76:77], v[60:61]
	s_nop 0
	v_add_f32_e32 v59, v65, v59
	v_mul_f32_e32 v58, v58, v59
	v_fmac_f32_e32 v66, v58, v58
	ds_bpermute_b32 v59, v188, v66
	v_cvt_pk_bf16_f32 v60, v62, v63
	v_cvt_pk_bf16_f32 v61, v64, v58
	s_waitcnt lgkmcnt(0)
	v_add_f32_e32 v58, v66, v59
	ds_bpermute_b32 v59, v189, v58
	global_store_dwordx2 v[78:79], v[60:61], off
	s_mov_b64 s[0:1], 0xc0000
	v_lshl_add_u64 v[78:79], v[78:79], 0, s[0:1]
	s_and_saveexec_b64 s[0:1], s[18:19]
	s_cbranch_execz .LBB0_719
	s_waitcnt lgkmcnt(0)
	v_add_f32_e32 v60, v58, v59
	global_store_dword v[90:91], v60, off offset:256
	s_branch .LBB0_719
